# norm_mod_bf loops (P1 layer 1, P5): the gain/scale/shift loads of a row issued as one batch instead of six at a time
# speedup vs baseline: 1.0115x; 1.0115x over previous
; __device__ __forceinline__ unsigned pk2(float lo, float hi) { const f32v2_t f = {lo, hi}; const bf16v2_t b = __builtin_convertvector(f, bf16v2_t); return __builtin_bit_cast(unsigned, b); }
; __device__ NOINL void norm_mod_bf_phase(const bf16_t* xb, int nrows, const float* g, const float* mod  , int si, bf16_t* hb) {
;     ...
;         for (int u = 0; u < 2; ++u)
;             if (rows[u] < nrows) {
;                 float v[2][8]; float ss = 0.f;
; #pragma unroll
;                 for (int j = 0; j < 2; ++j) { unpack8(q[u][j], v[j]);
; #pragma unroll
;                     for (int e = 0; e < 8; ++e) ss += v[j][e] * v[j][e]; }
;                 const float inv = rsqrtf(wave_sum(ss) * (1.f / DM) + 1e-6f);
;                 const float* sh = mod + (size_t)(rows[u] >> 11) * 6144 + si * 1024; const float* scp = sh + 1024;
; #pragma unroll
;                 for (int j = 0; j < 2; ++j) {
;                     const int c = 8 * lane + 512 * j;
;                     float o[8];
; #pragma unroll
;                     for (int h4 = 0; h4 < 2; ++h4) {
;                         const f32x4 gv = *(const f32x4*)(g + c + 4 * h4), sv = *(const f32x4*)(scp + c + 4 * h4), hv = *(const f32x4*)(sh + c + 4 * h4);
; #pragma unroll
;                         for (int e = 0; e < 4; ++e) o[4 * h4 + e] = v[j][4 * h4 + e] * inv * gv[e] * (1.f + sv[e]) + hv[e];
;                     }
;                     u32x4 pk; pk.x = pk2(o[0], o[1]); pk.y = pk2(o[2], o[3]); pk.z = pk2(o[4], o[5]); pk.w = pk2(o[6], o[7]);
;                     *(u32x4*)(hb + (size_t)rows[u] * DM + c) = pk;
;                 }
.LBB0_286:
	s_or_b64 exec, exec, s[46:47]
	v_ashrrev_i32_e32 v0, 11, v36
	v_readlane_b32 s0, v255, 30
	v_mul_hi_i32_i24_e32 v37, 0x6000, v0
	v_mul_i32_i24_e32 v36, 0x6000, v0
	v_readlane_b32 s1, v255, 31
	v_lshlrev_b32_e32 v0, 2, v2
	v_lshl_add_u64 v[36:37], s[0:1], 0, v[36:37]
	s_mov_b64 s[0:1], 0x1000
	v_lshl_add_u64 v[68:69], v[36:37], 0, s[0:1]
	v_lshl_add_u64 v[56:57], v[68:69], 0, v[0:1]
	v_lshl_add_u64 v[36:37], v[36:37], 0, v[0:1]
	global_load_dwordx4 v[44:47], v[26:27], off offset:16
	global_load_dwordx4 v[166:169], v[26:27], off
	global_load_dwordx4 v[170:173], v[56:57], off offset:16
	global_load_dwordx4 v[174:177], v[56:57], off
	global_load_dwordx4 v[178:181], v[36:37], off offset:16
	global_load_dwordx4 v[186:189], v[36:37], off
	v_mov_b32_e32 v183, v1
	v_mov_b32_e32 v182, v30
	v_lshl_add_u64 v[190:191], v[68:69], 0, v[182:183]
	global_load_dwordx4 v[192:195], v[28:29], off
	global_load_dwordx4 v[196:199], v[190:191], off
	global_load_dwordx4 v[234:237], v[28:29], off offset:16
	global_load_dwordx4 v[238:241], v[190:191], off offset:16
	global_load_dwordx4 v[242:245], v[36:37], off offset:2048
	global_load_dwordx4 v[246:249], v[36:37], off offset:2064
	s_waitcnt vmcnt(12)
	v_lshlrev_b32_e32 v80, 16, v20
	s_nop 0
	s_nop 0
	v_and_b32_e32 v81, 0xffff0000, v20
	v_lshlrev_b32_e32 v76, 16, v21
	v_and_b32_e32 v77, 0xffff0000, v21
	v_pk_mul_f32 v[20:21], v[80:81], v[80:81]
	v_pk_mul_f32 v[78:79], v[76:77], v[76:77]
	v_add_f32_e32 v20, v20, v21
	v_lshlrev_b32_e32 v74, 16, v22
	v_and_b32_e32 v75, 0xffff0000, v22
	v_add_f32_e32 v20, v78, v20
	v_lshlrev_b32_e32 v70, 16, v23
	v_and_b32_e32 v71, 0xffff0000, v23
	v_pk_mul_f32 v[22:23], v[74:75], v[74:75]
	v_add_f32_e32 v20, v79, v20
	v_add_f32_e32 v20, v22, v20
	v_pk_mul_f32 v[72:73], v[70:71], v[70:71]
	v_add_f32_e32 v20, v23, v20
	v_lshlrev_b32_e32 v92, 16, v16
	v_and_b32_e32 v93, 0xffff0000, v16
	v_add_f32_e32 v20, v72, v20
	v_lshlrev_b32_e32 v88, 16, v17
	v_and_b32_e32 v89, 0xffff0000, v17
	v_pk_mul_f32 v[16:17], v[92:93], v[92:93]
	v_add_f32_e32 v20, v73, v20
	v_add_f32_e32 v16, v16, v20
	v_pk_mul_f32 v[90:91], v[88:89], v[88:89]
	v_add_f32_e32 v16, v17, v16
	v_lshlrev_b32_e32 v86, 16, v18
	v_and_b32_e32 v87, 0xffff0000, v18
	v_add_f32_e32 v16, v90, v16
	v_lshlrev_b32_e32 v82, 16, v19
	v_and_b32_e32 v83, 0xffff0000, v19
	v_pk_mul_f32 v[18:19], v[86:87], v[86:87]
	v_add_f32_e32 v16, v91, v16
	v_add_f32_e32 v16, v18, v16
	v_pk_mul_f32 v[84:85], v[82:83], v[82:83]
	v_add_f32_e32 v16, v19, v16
	v_add_f32_e32 v16, v84, v16
	v_add_f32_e32 v16, v85, v16
	ds_bpermute_b32 v17, v3, v16
	s_waitcnt lgkmcnt(0)
	v_add_f32_e32 v16, v16, v17
	ds_bpermute_b32 v17, v38, v16
	s_waitcnt lgkmcnt(0)
	v_add_f32_e32 v16, v16, v17
	ds_bpermute_b32 v17, v39, v16
	s_waitcnt lgkmcnt(0)
	v_add_f32_e32 v16, v16, v17
	ds_bpermute_b32 v17, v40, v16
	s_waitcnt lgkmcnt(0)
	v_add_f32_e32 v16, v16, v17
	ds_bpermute_b32 v17, v41, v16
	s_waitcnt lgkmcnt(0)
	v_add_f32_e32 v16, v16, v17
	ds_bpermute_b32 v17, v42, v16
	s_waitcnt lgkmcnt(0)
	v_add_f32_e32 v16, v16, v17
	v_fmamk_f32 v16, v16, 0x3a800000, v211
	v_mul_f32_e32 v17, 0x4b800000, v16
	v_cmp_gt_f32_e64 s[46:47], s79, v16
	s_waitcnt vmcnt(9)
	v_pk_add_f32 v[22:23], v[170:171], 1.0 op_sel_hi:[1,0]
	v_cndmask_b32_e64 v16, v16, v17, s[46:47]
	v_rsq_f32_e32 v16, v16
	s_nop 0
	v_mul_f32_e32 v17, 0x45800000, v16
	v_cndmask_b32_e64 v72, v16, v17, s[46:47]
	v_pk_mul_f32 v[20:21], v[72:73], v[74:75] op_sel_hi:[0,1]
	v_pk_mul_f32 v[20:21], v[44:45], v[20:21]
	v_pk_mul_f32 v[16:17], v[72:73], v[80:81] op_sel_hi:[0,1]
	v_pk_mul_f32 v[18:19], v[72:73], v[76:77] op_sel_hi:[0,1]
	s_waitcnt vmcnt(7)
	v_pk_fma_f32 v[20:21], v[22:23], v[20:21], v[178:179]
	v_pk_mul_f32 v[22:23], v[72:73], v[70:71] op_sel_hi:[0,1]
	v_pk_mul_f32 v[16:17], v[166:167], v[16:17]
	v_pk_mul_f32 v[18:19], v[168:169], v[18:19]
	v_pk_add_f32 v[44:45], v[176:177], 1.0 op_sel_hi:[1,0]
	v_pk_add_f32 v[48:49], v[174:175], 1.0 op_sel_hi:[1,0]
	v_pk_add_f32 v[50:51], v[172:173], 1.0 op_sel_hi:[1,0]
	v_pk_mul_f32 v[22:23], v[46:47], v[22:23]
	s_waitcnt vmcnt(6)
	v_pk_fma_f32 v[16:17], v[48:49], v[16:17], v[186:187]
	v_pk_fma_f32 v[18:19], v[44:45], v[18:19], v[188:189]
	v_pk_fma_f32 v[22:23], v[50:51], v[22:23], v[180:181]
	v_cvt_pk_bf16_f32 v16, v16, v17
	v_cvt_pk_bf16_f32 v17, v18, v19
	v_cvt_pk_bf16_f32 v18, v20, v21
	v_cvt_pk_bf16_f32 v19, v22, v23
	global_store_dwordx4 v[34:35], v[16:19], off
	s_nop 0
	v_pk_mul_f32 v[36:37], v[72:73], v[92:93] op_sel_hi:[0,1]
	v_pk_mul_f32 v[60:61], v[72:73], v[88:89] op_sel_hi:[0,1]
	v_pk_mul_f32 v[62:63], v[72:73], v[86:87] op_sel_hi:[0,1]
	v_pk_mul_f32 v[64:65], v[72:73], v[82:83] op_sel_hi:[0,1]
	s_waitcnt vmcnt(6)
	v_pk_mul_f32 v[16:17], v[192:193], v[36:37]
	s_waitcnt vmcnt(5)
	v_pk_add_f32 v[20:21], v[196:197], 1.0 op_sel_hi:[1,0]
	v_pk_mul_f32 v[18:19], v[194:195], v[60:61]
	v_pk_add_f32 v[22:23], v[198:199], 1.0 op_sel_hi:[1,0]
	s_waitcnt vmcnt(4)
	v_pk_mul_f32 v[36:37], v[62:63], v[234:235]
	s_waitcnt vmcnt(3)
	v_pk_add_f32 v[44:45], v[238:239], 1.0 op_sel_hi:[1,0]
	v_pk_mul_f32 v[46:47], v[64:65], v[236:237]
	v_pk_add_f32 v[48:49], v[240:241], 1.0 op_sel_hi:[1,0]
	s_waitcnt vmcnt(2)
	v_pk_fma_f32 v[16:17], v[20:21], v[16:17], v[242:243]
	v_pk_fma_f32 v[18:19], v[22:23], v[18:19], v[244:245]
	s_waitcnt vmcnt(1)
	v_pk_fma_f32 v[20:21], v[36:37], v[44:45], v[246:247]
	v_pk_fma_f32 v[22:23], v[46:47], v[48:49], v[248:249]
	v_cvt_pk_bf16_f32 v16, v16, v17
	v_cvt_pk_bf16_f32 v17, v18, v19
	v_cvt_pk_bf16_f32 v18, v20, v21
	v_cvt_pk_bf16_f32 v19, v22, v23
	global_store_dwordx4 v[34:35], v[16:19], off offset:1024
	s_and_saveexec_b64 s[46:47], vcc
	s_cbranch_execz .LBB0_283
; __device__ __forceinline__ unsigned pk2(float lo, float hi) { const f32v2_t f = {lo, hi}; const bf16v2_t b = __builtin_convertvector(f, bf16v2_t); return __builtin_bit_cast(unsigned, b); }
; __device__ NOINL void norm_mod_bf_phase(const bf16_t* xb, int nrows, const float* g, const float* mod  , int si, bf16_t* hb) {
;     ...
;         for (int u = 0; u < 2; ++u)
;             if (rows[u] < nrows) {
;                 float v[2][8]; float ss = 0.f;
; #pragma unroll
;                 for (int j = 0; j < 2; ++j) { unpack8(q[u][j], v[j]);
; #pragma unroll
;                     for (int e = 0; e < 8; ++e) ss += v[j][e] * v[j][e]; }
;                 const float inv = rsqrtf(wave_sum(ss) * (1.f / DM) + 1e-6f);
;                 const float* sh = mod + (size_t)(rows[u] >> 11) * 6144 + si * 1024; const float* scp = sh + 1024;
; #pragma unroll
;                 for (int j = 0; j < 2; ++j) {
;                     const int c = 8 * lane + 512 * j;
;                     float o[8];
; #pragma unroll
;                     for (int h4 = 0; h4 < 2; ++h4) {
;                         const f32x4 gv = *(const f32x4*)(g + c + 4 * h4), sv = *(const f32x4*)(scp + c + 4 * h4), hv = *(const f32x4*)(sh + c + 4 * h4);
; #pragma unroll
;                         for (int e = 0; e < 4; ++e) o[4 * h4 + e] = v[j][4 * h4 + e] * inv * gv[e] * (1.f + sv[e]) + hv[e];
;                     }
;                     u32x4 pk; pk.x = pk2(o[0], o[1]); pk.y = pk2(o[2], o[3]); pk.z = pk2(o[4], o[5]); pk.w = pk2(o[6], o[7]);
;                     *(u32x4*)(hb + (size_t)rows[u] * DM + c) = pk;
;                 }
	v_ashrrev_i32_e32 v16, 11, v32
	v_readlane_b32 s0, v255, 30
	v_mul_hi_i32_i24_e32 v17, 0x6000, v16
	v_mul_i32_i24_e32 v16, 0x6000, v16
	v_readlane_b32 s1, v255, 31
	v_lshlrev_b32_e32 v72, 16, v12
	v_and_b32_e32 v73, 0xffff0000, v12
	v_lshl_add_u64 v[16:17], s[0:1], 0, v[16:17]
	s_mov_b64 s[0:1], 0x1000
	v_lshl_add_u64 v[56:57], v[16:17], 0, s[0:1]
	v_lshl_add_u64 v[44:45], v[56:57], 0, v[0:1]
	v_lshl_add_u64 v[58:59], v[16:17], 0, v[0:1]
	global_load_dwordx4 v[166:169], v[26:27], off offset:16
	global_load_dwordx4 v[170:173], v[26:27], off
	global_load_dwordx4 v[174:177], v[44:45], off offset:16
	global_load_dwordx4 v[178:181], v[44:45], off
	global_load_dwordx4 v[186:189], v[58:59], off offset:16
	global_load_dwordx4 v[190:193], v[58:59], off
	v_mov_b32_e32 v31, v1
	v_lshl_add_u64 v[182:183], v[56:57], 0, v[30:31]
	global_load_dwordx4 v[194:197], v[28:29], off
	global_load_dwordx4 v[198:201], v[182:183], off
	global_load_dwordx4 v[234:237], v[28:29], off offset:16
	global_load_dwordx4 v[238:241], v[182:183], off offset:16
	global_load_dwordx4 v[242:245], v[58:59], off offset:2048
	global_load_dwordx4 v[246:249], v[58:59], off offset:2064
	s_nop 0
	s_nop 0
	v_lshlrev_b32_e32 v68, 16, v13
	v_and_b32_e32 v69, 0xffff0000, v13
	v_pk_mul_f32 v[74:75], v[72:73], v[72:73]
	v_pk_mul_f32 v[70:71], v[68:69], v[68:69]
	v_add_f32_e32 v0, v74, v75
	v_lshlrev_b32_e32 v64, 16, v14
	v_and_b32_e32 v65, 0xffff0000, v14
	v_add_f32_e32 v0, v70, v0
	v_pk_mul_f32 v[66:67], v[64:65], v[64:65]
	v_add_f32_e32 v0, v71, v0
	v_lshlrev_b32_e32 v60, 16, v15
	v_and_b32_e32 v61, 0xffff0000, v15
	v_add_f32_e32 v0, v66, v0
	v_pk_mul_f32 v[62:63], v[60:61], v[60:61]
	v_add_f32_e32 v0, v67, v0
	v_lshlrev_b32_e32 v88, 16, v8
	v_and_b32_e32 v89, 0xffff0000, v8
	v_add_f32_e32 v0, v62, v0
	v_pk_mul_f32 v[90:91], v[88:89], v[88:89]
	v_add_f32_e32 v0, v63, v0
	v_lshlrev_b32_e32 v84, 16, v9
	v_and_b32_e32 v85, 0xffff0000, v9
	v_add_f32_e32 v0, v90, v0
	v_pk_mul_f32 v[86:87], v[84:85], v[84:85]
	v_add_f32_e32 v0, v91, v0
	v_lshlrev_b32_e32 v80, 16, v10
	v_and_b32_e32 v81, 0xffff0000, v10
	v_add_f32_e32 v0, v86, v0
	v_pk_mul_f32 v[82:83], v[80:81], v[80:81]
	v_add_f32_e32 v0, v87, v0
	v_lshlrev_b32_e32 v76, 16, v11
	v_and_b32_e32 v77, 0xffff0000, v11
	v_add_f32_e32 v0, v82, v0
	v_pk_mul_f32 v[78:79], v[76:77], v[76:77]
	v_add_f32_e32 v0, v83, v0
	v_add_f32_e32 v0, v78, v0
	v_add_f32_e32 v0, v79, v0
	ds_bpermute_b32 v43, v3, v0
	v_lshlrev_b64 v[62:63], 11, v[32:33]
	v_lshl_add_u64 v[62:63], v[24:25], 0, v[62:63]
	s_waitcnt lgkmcnt(0)
	v_add_f32_e32 v0, v0, v43
	ds_bpermute_b32 v43, v38, v0
	s_waitcnt lgkmcnt(0)
	v_add_f32_e32 v0, v0, v43
	ds_bpermute_b32 v43, v39, v0
	s_waitcnt lgkmcnt(0)
	v_add_f32_e32 v0, v0, v43
	ds_bpermute_b32 v43, v40, v0
	s_waitcnt lgkmcnt(0)
	v_add_f32_e32 v0, v0, v43
	ds_bpermute_b32 v43, v41, v0
	s_waitcnt lgkmcnt(0)
	v_add_f32_e32 v0, v0, v43
	ds_bpermute_b32 v43, v42, v0
	s_waitcnt lgkmcnt(0)
	v_add_f32_e32 v0, v0, v43
	v_fmamk_f32 v0, v0, 0x3a800000, v211
	v_mul_f32_e32 v43, 0x4b800000, v0
	v_cmp_gt_f32_e32 vcc, s79, v0
	s_waitcnt vmcnt(9)
	v_pk_add_f32 v[34:35], v[174:175], 1.0 op_sel_hi:[1,0]
	s_waitcnt vmcnt(8)
	v_pk_add_f32 v[46:47], v[180:181], 1.0 op_sel_hi:[1,0]
	v_cndmask_b32_e32 v0, v0, v43, vcc
	v_rsq_f32_e32 v0, v0
	v_pk_add_f32 v[44:45], v[178:179], 1.0 op_sel_hi:[1,0]
	v_pk_add_f32 v[36:37], v[176:177], 1.0 op_sel_hi:[1,0]
	v_mul_f32_e32 v31, 0x45800000, v0
	v_cndmask_b32_e32 v0, v0, v31, vcc
	v_pk_mul_f32 v[64:65], v[0:1], v[64:65] op_sel_hi:[0,1]
	v_pk_mul_f32 v[16:17], v[166:167], v[64:65]
	v_pk_mul_f32 v[66:67], v[0:1], v[72:73] op_sel_hi:[0,1]
	v_pk_mul_f32 v[68:69], v[0:1], v[68:69] op_sel_hi:[0,1]
	s_waitcnt vmcnt(7)
	v_pk_fma_f32 v[34:35], v[34:35], v[16:17], v[186:187]
	v_pk_mul_f32 v[16:17], v[0:1], v[60:61] op_sel_hi:[0,1]
	v_pk_mul_f32 v[20:21], v[170:171], v[66:67]
	v_pk_mul_f32 v[22:23], v[172:173], v[68:69]
	v_pk_mul_f32 v[16:17], v[168:169], v[16:17]
	s_waitcnt vmcnt(6)
	v_pk_fma_f32 v[20:21], v[44:45], v[20:21], v[190:191]
	v_pk_fma_f32 v[22:23], v[46:47], v[22:23], v[192:193]
	v_pk_fma_f32 v[36:37], v[36:37], v[16:17], v[188:189]
	v_cvt_pk_bf16_f32 v16, v20, v21
	v_cvt_pk_bf16_f32 v17, v22, v23
	v_cvt_pk_bf16_f32 v18, v34, v35
	v_cvt_pk_bf16_f32 v19, v36, v37
	global_store_dwordx4 v[62:63], v[16:19], off
	s_nop 0
	v_pk_mul_f32 v[56:57], v[0:1], v[88:89] op_sel_hi:[0,1]
	v_pk_mul_f32 v[58:59], v[0:1], v[84:85] op_sel_hi:[0,1]
	v_pk_mul_f32 v[60:61], v[0:1], v[80:81] op_sel_hi:[0,1]
	v_pk_mul_f32 v[64:65], v[0:1], v[76:77] op_sel_hi:[0,1]
	s_waitcnt vmcnt(6)
	v_pk_mul_f32 v[16:17], v[194:195], v[56:57]
	s_waitcnt vmcnt(5)
	v_pk_add_f32 v[20:21], v[198:199], 1.0 op_sel_hi:[1,0]
	v_pk_mul_f32 v[18:19], v[196:197], v[58:59]
	v_pk_add_f32 v[22:23], v[200:201], 1.0 op_sel_hi:[1,0]
	s_waitcnt vmcnt(4)
	v_pk_mul_f32 v[34:35], v[60:61], v[234:235]
	s_waitcnt vmcnt(3)
	v_pk_add_f32 v[44:45], v[238:239], 1.0 op_sel_hi:[1,0]
	v_pk_mul_f32 v[36:37], v[64:65], v[236:237]
	v_pk_add_f32 v[46:47], v[240:241], 1.0 op_sel_hi:[1,0]
	s_waitcnt vmcnt(2)
	v_pk_fma_f32 v[16:17], v[20:21], v[16:17], v[242:243]
	v_pk_fma_f32 v[18:19], v[22:23], v[18:19], v[244:245]
	s_waitcnt vmcnt(1)
	v_pk_fma_f32 v[20:21], v[34:35], v[44:45], v[246:247]
	v_pk_fma_f32 v[22:23], v[36:37], v[46:47], v[248:249]
	v_cvt_pk_bf16_f32 v16, v16, v17
	v_cvt_pk_bf16_f32 v17, v18, v19
	v_cvt_pk_bf16_f32 v18, v20, v21
	v_cvt_pk_bf16_f32 v19, v22, v23
	global_store_dwordx4 v[62:63], v[16:19], off offset:1024
	s_branch .LBB0_283

; __device__ __forceinline__ unsigned pk2(float lo, float hi) { const f32v2_t f = {lo, hi}; const bf16v2_t b = __builtin_convertvector(f, bf16v2_t); return __builtin_bit_cast(unsigned, b); }
; __device__ NOINL void norm_mod_bf_phase(const bf16_t* xb, int nrows, const float* g, const float* mod  , int si, bf16_t* hb) {
;     ...
;         for (int u = 0; u < 2; ++u)
;             if (rows[u] < nrows) {
;                 float v[2][8]; float ss = 0.f;
; #pragma unroll
;                 for (int j = 0; j < 2; ++j) { unpack8(q[u][j], v[j]);
; #pragma unroll
;                     for (int e = 0; e < 8; ++e) ss += v[j][e] * v[j][e]; }
;                 const float inv = rsqrtf(wave_sum(ss) * (1.f / DM) + 1e-6f);
;                 const float* sh = mod + (size_t)(rows[u] >> 11) * 6144 + si * 1024; const float* scp = sh + 1024;
; #pragma unroll
;                 for (int j = 0; j < 2; ++j) {
;                     const int c = 8 * lane + 512 * j;
;                     float o[8];
; #pragma unroll
;                     for (int h4 = 0; h4 < 2; ++h4) {
;                         const f32x4 gv = *(const f32x4*)(g + c + 4 * h4), sv = *(const f32x4*)(scp + c + 4 * h4), hv = *(const f32x4*)(sh + c + 4 * h4);
; #pragma unroll
;                         for (int e = 0; e < 4; ++e) o[4 * h4 + e] = v[j][4 * h4 + e] * inv * gv[e] * (1.f + sv[e]) + hv[e];
;                     }
;                     u32x4 pk; pk.x = pk2(o[0], o[1]); pk.y = pk2(o[2], o[3]); pk.z = pk2(o[4], o[5]); pk.w = pk2(o[6], o[7]);
;                     *(u32x4*)(hb + (size_t)rows[u] * DM + c) = pk;
;                 }
.LBB0_1635:
	s_or_b64 exec, exec, s[44:45]
	v_ashrrev_i32_e32 v0, 11, v36
	v_mul_hi_i32_i24_e32 v37, 0x6000, v0
	v_mul_i32_i24_e32 v36, 0x6000, v0
	v_lshl_add_u64 v[36:37], s[48:49], 0, v[36:37]
	s_mov_b64 s[0:1], 0x1000
	v_lshl_add_u64 v[68:69], v[36:37], 0, s[0:1]
	v_lshlrev_b32_e32 v0, 2, v2
	v_lshl_add_u64 v[56:57], v[68:69], 0, v[0:1]
	v_lshl_add_u64 v[70:71], v[36:37], 0, v[0:1]
	global_load_dwordx4 v[44:47], v[26:27], off offset:16
	global_load_dwordx4 v[48:51], v[26:27], off
	global_load_dwordx4 v[52:55], v[56:57], off offset:16
	s_nop 0
	global_load_dwordx4 v[56:59], v[56:57], off
	s_nop 0
	global_load_dwordx4 v[60:63], v[70:71], off offset:16
	global_load_dwordx4 v[64:67], v[70:71], off
	s_waitcnt vmcnt(0)
	v_mov_b32_e32 v167, v1
	v_mov_b32_e32 v166, v30
	v_lshl_add_u64 v[168:169], v[68:69], 0, v[166:167]
	global_load_dwordx4 v[170:173], v[26:27], off offset:2048
	global_load_dwordx4 v[174:177], v[168:169], off
	global_load_dwordx4 v[178:181], v[26:27], off offset:2064
	global_load_dwordx4 v[186:189], v[168:169], off offset:16
	global_load_dwordx4 v[166:169], v[70:71], off offset:2048
	global_load_dwordx4 v[190:193], v[70:71], off offset:2064
	v_lshlrev_b32_e32 v80, 16, v20
	v_and_b32_e32 v81, 0xffff0000, v20
	v_lshlrev_b32_e32 v76, 16, v21
	v_and_b32_e32 v77, 0xffff0000, v21
	v_pk_mul_f32 v[20:21], v[80:81], v[80:81]
	v_pk_mul_f32 v[78:79], v[76:77], v[76:77]
	v_add_f32_e32 v20, v20, v21
	v_lshlrev_b32_e32 v74, 16, v22
	v_and_b32_e32 v75, 0xffff0000, v22
	v_add_f32_e32 v20, v78, v20
	v_lshlrev_b32_e32 v36, 16, v23
	v_and_b32_e32 v37, 0xffff0000, v23
	v_pk_mul_f32 v[22:23], v[74:75], v[74:75]
	v_add_f32_e32 v20, v79, v20
	v_add_f32_e32 v20, v22, v20
	v_pk_mul_f32 v[72:73], v[36:37], v[36:37]
	v_add_f32_e32 v20, v23, v20
	v_lshlrev_b32_e32 v92, 16, v16
	v_and_b32_e32 v93, 0xffff0000, v16
	v_add_f32_e32 v20, v72, v20
	v_lshlrev_b32_e32 v88, 16, v17
	v_and_b32_e32 v89, 0xffff0000, v17
	v_pk_mul_f32 v[16:17], v[92:93], v[92:93]
	v_add_f32_e32 v20, v73, v20
	v_add_f32_e32 v16, v16, v20
	v_pk_mul_f32 v[90:91], v[88:89], v[88:89]
	v_add_f32_e32 v16, v17, v16
	v_lshlrev_b32_e32 v86, 16, v18
	v_and_b32_e32 v87, 0xffff0000, v18
	v_add_f32_e32 v16, v90, v16
	v_lshlrev_b32_e32 v82, 16, v19
	v_and_b32_e32 v83, 0xffff0000, v19
	v_pk_mul_f32 v[18:19], v[86:87], v[86:87]
	v_add_f32_e32 v16, v91, v16
	v_add_f32_e32 v16, v18, v16
	v_pk_mul_f32 v[84:85], v[82:83], v[82:83]
	v_add_f32_e32 v16, v19, v16
	v_add_f32_e32 v16, v84, v16
	v_add_f32_e32 v16, v85, v16
	ds_bpermute_b32 v17, v3, v16
	v_lshl_add_u64 v[72:73], v[28:29], 0, v[34:35]
	s_waitcnt lgkmcnt(0)
	v_add_f32_e32 v16, v16, v17
	ds_bpermute_b32 v17, v38, v16
	s_waitcnt lgkmcnt(0)
	v_add_f32_e32 v16, v16, v17
	ds_bpermute_b32 v17, v39, v16
	s_waitcnt lgkmcnt(0)
	v_add_f32_e32 v16, v16, v17
	ds_bpermute_b32 v17, v40, v16
	s_waitcnt lgkmcnt(0)
	v_add_f32_e32 v16, v16, v17
	ds_bpermute_b32 v17, v41, v16
	s_waitcnt lgkmcnt(0)
	v_add_f32_e32 v16, v16, v17
	ds_bpermute_b32 v17, v42, v16
	s_waitcnt lgkmcnt(0)
	v_add_f32_e32 v16, v16, v17
	v_fmamk_f32 v16, v16, 0x3a800000, v211
	v_mul_f32_e32 v17, 0x4b800000, v16
	v_cmp_gt_f32_e64 s[44:45], s79, v16
	v_pk_add_f32 v[22:23], v[52:53], 1.0 op_sel_hi:[1,0]
	v_pk_add_f32 v[34:35], v[58:59], 1.0 op_sel_hi:[1,0]
	v_cndmask_b32_e64 v16, v16, v17, s[44:45]
	v_rsq_f32_e32 v16, v16
	s_nop 0
	v_mul_f32_e32 v17, 0x45800000, v16
	v_cndmask_b32_e64 v78, v16, v17, s[44:45]
	v_pk_mul_f32 v[20:21], v[78:79], v[74:75] op_sel_hi:[0,1]
	v_pk_mul_f32 v[20:21], v[44:45], v[20:21]
	v_pk_mul_f32 v[16:17], v[78:79], v[80:81] op_sel_hi:[0,1]
	v_pk_mul_f32 v[18:19], v[78:79], v[76:77] op_sel_hi:[0,1]
	v_pk_fma_f32 v[20:21], v[22:23], v[20:21], v[60:61]
	v_pk_mul_f32 v[22:23], v[78:79], v[36:37] op_sel_hi:[0,1]
	v_pk_mul_f32 v[16:17], v[48:49], v[16:17]
	v_pk_mul_f32 v[18:19], v[50:51], v[18:19]
	v_pk_add_f32 v[44:45], v[56:57], 1.0 op_sel_hi:[1,0]
	v_pk_add_f32 v[48:49], v[54:55], 1.0 op_sel_hi:[1,0]
	v_pk_mul_f32 v[22:23], v[46:47], v[22:23]
	v_pk_fma_f32 v[16:17], v[44:45], v[16:17], v[64:65]
	v_pk_fma_f32 v[18:19], v[34:35], v[18:19], v[66:67]
	v_pk_fma_f32 v[22:23], v[48:49], v[22:23], v[62:63]
	v_cvt_pk_bf16_f32 v16, v16, v17
	v_cvt_pk_bf16_f32 v17, v18, v19
	v_cvt_pk_bf16_f32 v18, v20, v21
	v_cvt_pk_bf16_f32 v19, v22, v23
	global_store_dwordx4 v[72:73], v[16:19], off
	s_nop 0
	v_pk_mul_f32 v[56:57], v[78:79], v[92:93] op_sel_hi:[0,1]
	v_pk_mul_f32 v[58:59], v[78:79], v[88:89] op_sel_hi:[0,1]
	v_pk_mul_f32 v[60:61], v[78:79], v[86:87] op_sel_hi:[0,1]
	v_pk_mul_f32 v[62:63], v[78:79], v[82:83] op_sel_hi:[0,1]
	s_waitcnt vmcnt(6)
	v_pk_mul_f32 v[16:17], v[170:171], v[56:57]
	s_waitcnt vmcnt(5)
	v_pk_add_f32 v[20:21], v[174:175], 1.0 op_sel_hi:[1,0]
	v_pk_mul_f32 v[18:19], v[172:173], v[58:59]
	v_pk_add_f32 v[22:23], v[176:177], 1.0 op_sel_hi:[1,0]
	s_waitcnt vmcnt(4)
	v_pk_mul_f32 v[34:35], v[60:61], v[178:179]
	s_waitcnt vmcnt(3)
	v_pk_add_f32 v[44:45], v[186:187], 1.0 op_sel_hi:[1,0]
	v_pk_mul_f32 v[36:37], v[62:63], v[180:181]
	v_pk_add_f32 v[46:47], v[188:189], 1.0 op_sel_hi:[1,0]
	s_waitcnt vmcnt(2)
	v_pk_fma_f32 v[16:17], v[20:21], v[16:17], v[166:167]
	v_pk_fma_f32 v[18:19], v[22:23], v[18:19], v[168:169]
	s_waitcnt vmcnt(1)
	v_pk_fma_f32 v[20:21], v[34:35], v[44:45], v[190:191]
	v_pk_fma_f32 v[22:23], v[36:37], v[46:47], v[192:193]
	v_cvt_pk_bf16_f32 v16, v16, v17
	v_cvt_pk_bf16_f32 v17, v18, v19
	v_cvt_pk_bf16_f32 v18, v20, v21
	v_cvt_pk_bf16_f32 v19, v22, v23
	global_store_dwordx4 v[72:73], v[16:19], off offset:1024
	s_and_saveexec_b64 s[44:45], vcc
	s_cbranch_execz .LBB0_1632
; __device__ __forceinline__ unsigned pk2(float lo, float hi) { const f32v2_t f = {lo, hi}; const bf16v2_t b = __builtin_convertvector(f, bf16v2_t); return __builtin_bit_cast(unsigned, b); }
; __device__ NOINL void norm_mod_bf_phase(const bf16_t* xb, int nrows, const float* g, const float* mod  , int si, bf16_t* hb) {
;     ...
;         for (int u = 0; u < 2; ++u)
;             if (rows[u] < nrows) {
;                 float v[2][8]; float ss = 0.f;
; #pragma unroll
;                 for (int j = 0; j < 2; ++j) { unpack8(q[u][j], v[j]);
; #pragma unroll
;                     for (int e = 0; e < 8; ++e) ss += v[j][e] * v[j][e]; }
;                 const float inv = rsqrtf(wave_sum(ss) * (1.f / DM) + 1e-6f);
;                 const float* sh = mod + (size_t)(rows[u] >> 11) * 6144 + si * 1024; const float* scp = sh + 1024;
; #pragma unroll
;                 for (int j = 0; j < 2; ++j) {
;                     const int c = 8 * lane + 512 * j;
;                     float o[8];
; #pragma unroll
;                     for (int h4 = 0; h4 < 2; ++h4) {
;                         const f32x4 gv = *(const f32x4*)(g + c + 4 * h4), sv = *(const f32x4*)(scp + c + 4 * h4), hv = *(const f32x4*)(sh + c + 4 * h4);
; #pragma unroll
;                         for (int e = 0; e < 4; ++e) o[4 * h4 + e] = v[j][4 * h4 + e] * inv * gv[e] * (1.f + sv[e]) + hv[e];
;                     }
;                     u32x4 pk; pk.x = pk2(o[0], o[1]); pk.y = pk2(o[2], o[3]); pk.z = pk2(o[4], o[5]); pk.w = pk2(o[6], o[7]);
;                     *(u32x4*)(hb + (size_t)rows[u] * DM + c) = pk;
;                 }
	v_ashrrev_i32_e32 v16, 11, v32
	v_mul_hi_i32_i24_e32 v17, 0x6000, v16
	v_mul_i32_i24_e32 v16, 0x6000, v16
	v_lshl_add_u64 v[16:17], s[48:49], 0, v[16:17]
	v_lshl_add_u64 v[56:57], v[16:17], 0, s[0:1]
	v_lshl_add_u64 v[44:45], v[56:57], 0, v[0:1]
	v_lshl_add_u64 v[58:59], v[16:17], 0, v[0:1]
	global_load_dwordx4 v[166:169], v[26:27], off offset:16
	global_load_dwordx4 v[170:173], v[26:27], off
	global_load_dwordx4 v[174:177], v[44:45], off offset:16
	global_load_dwordx4 v[178:181], v[44:45], off
	global_load_dwordx4 v[186:189], v[58:59], off offset:16
	global_load_dwordx4 v[190:193], v[58:59], off
	v_mov_b32_e32 v31, v1
	v_lshl_add_u64 v[182:183], v[56:57], 0, v[30:31]
	global_load_dwordx4 v[194:197], v[26:27], off offset:2048
	global_load_dwordx4 v[198:201], v[182:183], off
	global_load_dwordx4 v[234:237], v[26:27], off offset:2064
	global_load_dwordx4 v[238:241], v[182:183], off offset:16
	global_load_dwordx4 v[242:245], v[58:59], off offset:2048
	global_load_dwordx4 v[246:249], v[58:59], off offset:2064
	s_nop 0
	s_nop 0
	v_lshlrev_b32_e32 v72, 16, v12
	v_and_b32_e32 v73, 0xffff0000, v12
	v_lshlrev_b32_e32 v68, 16, v13
	v_and_b32_e32 v69, 0xffff0000, v13
	v_pk_mul_f32 v[74:75], v[72:73], v[72:73]
	v_pk_mul_f32 v[70:71], v[68:69], v[68:69]
	v_add_f32_e32 v0, v74, v75
	v_lshlrev_b32_e32 v64, 16, v14
	v_and_b32_e32 v65, 0xffff0000, v14
	v_add_f32_e32 v0, v70, v0
	v_pk_mul_f32 v[66:67], v[64:65], v[64:65]
	v_add_f32_e32 v0, v71, v0
	v_lshlrev_b32_e32 v60, 16, v15
	v_and_b32_e32 v61, 0xffff0000, v15
	v_add_f32_e32 v0, v66, v0
	v_pk_mul_f32 v[62:63], v[60:61], v[60:61]
	v_add_f32_e32 v0, v67, v0
	v_lshlrev_b32_e32 v88, 16, v8
	v_and_b32_e32 v89, 0xffff0000, v8
	v_add_f32_e32 v0, v62, v0
	v_pk_mul_f32 v[90:91], v[88:89], v[88:89]
	v_add_f32_e32 v0, v63, v0
	v_lshlrev_b32_e32 v84, 16, v9
	v_and_b32_e32 v85, 0xffff0000, v9
	v_add_f32_e32 v0, v90, v0
	v_pk_mul_f32 v[86:87], v[84:85], v[84:85]
	v_add_f32_e32 v0, v91, v0
	v_lshlrev_b32_e32 v80, 16, v10
	v_and_b32_e32 v81, 0xffff0000, v10
	v_add_f32_e32 v0, v86, v0
	v_pk_mul_f32 v[82:83], v[80:81], v[80:81]
	v_add_f32_e32 v0, v87, v0
	v_lshlrev_b32_e32 v76, 16, v11
	v_and_b32_e32 v77, 0xffff0000, v11
	v_add_f32_e32 v0, v82, v0
	v_pk_mul_f32 v[78:79], v[76:77], v[76:77]
	v_add_f32_e32 v0, v83, v0
	v_add_f32_e32 v0, v78, v0
	v_add_f32_e32 v0, v79, v0
	ds_bpermute_b32 v43, v3, v0
	v_lshlrev_b64 v[62:63], 11, v[32:33]
	v_lshl_add_u64 v[62:63], v[28:29], 0, v[62:63]
	s_waitcnt lgkmcnt(0)
	v_add_f32_e32 v0, v0, v43
	ds_bpermute_b32 v43, v38, v0
	s_waitcnt lgkmcnt(0)
	v_add_f32_e32 v0, v0, v43
	ds_bpermute_b32 v43, v39, v0
	s_waitcnt lgkmcnt(0)
	v_add_f32_e32 v0, v0, v43
	ds_bpermute_b32 v43, v40, v0
	s_waitcnt lgkmcnt(0)
	v_add_f32_e32 v0, v0, v43
	ds_bpermute_b32 v43, v41, v0
	s_waitcnt lgkmcnt(0)
	v_add_f32_e32 v0, v0, v43
	ds_bpermute_b32 v43, v42, v0
	s_waitcnt lgkmcnt(0)
	v_add_f32_e32 v0, v0, v43
	v_fmamk_f32 v0, v0, 0x3a800000, v211
	v_mul_f32_e32 v43, 0x4b800000, v0
	v_cmp_gt_f32_e32 vcc, s79, v0
	s_waitcnt vmcnt(9)
	v_pk_add_f32 v[34:35], v[174:175], 1.0 op_sel_hi:[1,0]
	s_waitcnt vmcnt(8)
	v_pk_add_f32 v[46:47], v[180:181], 1.0 op_sel_hi:[1,0]
	v_cndmask_b32_e32 v0, v0, v43, vcc
	v_rsq_f32_e32 v0, v0
	v_pk_add_f32 v[44:45], v[178:179], 1.0 op_sel_hi:[1,0]
	v_pk_add_f32 v[36:37], v[176:177], 1.0 op_sel_hi:[1,0]
	v_mul_f32_e32 v31, 0x45800000, v0
	v_cndmask_b32_e32 v0, v0, v31, vcc
	v_pk_mul_f32 v[64:65], v[0:1], v[64:65] op_sel_hi:[0,1]
	v_pk_mul_f32 v[16:17], v[166:167], v[64:65]
	v_pk_mul_f32 v[66:67], v[0:1], v[72:73] op_sel_hi:[0,1]
	v_pk_mul_f32 v[68:69], v[0:1], v[68:69] op_sel_hi:[0,1]
	s_waitcnt vmcnt(7)
	v_pk_fma_f32 v[34:35], v[34:35], v[16:17], v[186:187]
	v_pk_mul_f32 v[16:17], v[0:1], v[60:61] op_sel_hi:[0,1]
	v_pk_mul_f32 v[20:21], v[170:171], v[66:67]
	v_pk_mul_f32 v[22:23], v[172:173], v[68:69]
	v_pk_mul_f32 v[16:17], v[168:169], v[16:17]
	s_waitcnt vmcnt(6)
	v_pk_fma_f32 v[20:21], v[44:45], v[20:21], v[190:191]
	v_pk_fma_f32 v[22:23], v[46:47], v[22:23], v[192:193]
	v_pk_fma_f32 v[36:37], v[36:37], v[16:17], v[188:189]
	v_cvt_pk_bf16_f32 v16, v20, v21
	v_cvt_pk_bf16_f32 v17, v22, v23
	v_cvt_pk_bf16_f32 v18, v34, v35
	v_cvt_pk_bf16_f32 v19, v36, v37
	global_store_dwordx4 v[62:63], v[16:19], off
	s_nop 0
	v_pk_mul_f32 v[56:57], v[0:1], v[88:89] op_sel_hi:[0,1]
	v_pk_mul_f32 v[58:59], v[0:1], v[84:85] op_sel_hi:[0,1]
	v_pk_mul_f32 v[60:61], v[0:1], v[80:81] op_sel_hi:[0,1]
	v_pk_mul_f32 v[64:65], v[0:1], v[76:77] op_sel_hi:[0,1]
	s_waitcnt vmcnt(6)
	v_pk_mul_f32 v[16:17], v[194:195], v[56:57]
	s_waitcnt vmcnt(5)
	v_pk_add_f32 v[20:21], v[198:199], 1.0 op_sel_hi:[1,0]
	v_pk_mul_f32 v[18:19], v[196:197], v[58:59]
	v_pk_add_f32 v[22:23], v[200:201], 1.0 op_sel_hi:[1,0]
	s_waitcnt vmcnt(4)
	v_pk_mul_f32 v[34:35], v[60:61], v[234:235]
	s_waitcnt vmcnt(3)
	v_pk_add_f32 v[44:45], v[238:239], 1.0 op_sel_hi:[1,0]
	v_pk_mul_f32 v[36:37], v[64:65], v[236:237]
	v_pk_add_f32 v[46:47], v[240:241], 1.0 op_sel_hi:[1,0]
	s_waitcnt vmcnt(2)
	v_pk_fma_f32 v[16:17], v[20:21], v[16:17], v[242:243]
	v_pk_fma_f32 v[18:19], v[22:23], v[18:19], v[244:245]
	s_waitcnt vmcnt(1)
	v_pk_fma_f32 v[20:21], v[34:35], v[44:45], v[246:247]
	v_pk_fma_f32 v[22:23], v[36:37], v[46:47], v[248:249]
	v_cvt_pk_bf16_f32 v16, v16, v17
	v_cvt_pk_bf16_f32 v17, v18, v19
	v_cvt_pk_bf16_f32 v18, v20, v21
	v_cvt_pk_bf16_f32 v19, v22, v23
	global_store_dwordx4 v[62:63], v[16:19], off offset:1024
	s_branch .LBB0_1632
